# P3 GLU sample row block (the pole of P3): gate functor's eight loads issued ahead of its four iterations (was load-wait-compute four times)
# baseline (speedup 1.0000x reference)
; #define LAS __attribute__((address_space(3)))
;     ...
; #pragma unroll 1
;     for (int e = tid; e < 16 * MB * (TN / 4); e += NWAVES * 64) { const int row = e / (TN / 4), c4 = 4 * (e % (TN / 4));
;         f32x4 v = *(const LAS f32x4*)(red + (size_t)(row * P + c4));
; #pragma unroll
;         for (int w = 1; w < WK; ++w) v = v + *(const LAS f32x4*)(red + (size_t)((w * 16 * MB + row) * P + c4));
;         if constexpr (ONEPASS) f(row, c4, v, pre); else f(row, c4, v, f.prefetch(row, c4)); }
.LBB0_1068:
	v_ashrrev_i32_e32 v6, 31, v5
	v_lshrrev_b32_e32 v6, 25, v6
	v_add_u32_e32 v6, v5, v6
	v_ashrrev_i32_e32 v218, 7, v6
	v_lshlrev_b32_e32 v7, 9, v218
	v_add_u32_e32 v6, s27, v218
	v_sub_u32_e32 v10, v2, v7
	v_ashrrev_i32_e32 v7, 31, v6
	v_lshlrev_b64 v[6:7], 10, v[6:7]
	v_ashrrev_i32_e32 v11, 31, v10
	v_lshl_add_u64 v[12:13], s[8:9], 0, v[6:7]
	v_lshl_add_u64 v[6:7], v[10:11], 2, s[4:5]
	global_load_dwordx4 v[212:215], v[6:7], off
	v_lshl_add_u64 v[10:11], v[10:11], 1, v[12:13]
	global_load_dwordx2 v[216:217], v[10:11], off
	v_add_u32_e32 v243, 0x200, v5
	v_add_u32_e32 v244, 0x800, v2
	v_ashrrev_i32_e32 v6, 31, v243
	v_lshrrev_b32_e32 v6, 25, v6
	v_add_u32_e32 v6, v243, v6
	v_ashrrev_i32_e32 v226, 7, v6
	v_lshlrev_b32_e32 v7, 9, v226
	v_add_u32_e32 v6, s27, v226
	v_sub_u32_e32 v10, v244, v7
	v_ashrrev_i32_e32 v7, 31, v6
	v_lshlrev_b64 v[6:7], 10, v[6:7]
	v_ashrrev_i32_e32 v11, 31, v10
	v_lshl_add_u64 v[12:13], s[8:9], 0, v[6:7]
	v_lshl_add_u64 v[6:7], v[10:11], 2, s[4:5]
	global_load_dwordx4 v[220:223], v[6:7], off
	v_lshl_add_u64 v[10:11], v[10:11], 1, v[12:13]
	global_load_dwordx2 v[224:225], v[10:11], off
	v_add_u32_e32 v243, 0x400, v5
	v_add_u32_e32 v244, 0x1000, v2
	v_ashrrev_i32_e32 v6, 31, v243
	v_lshrrev_b32_e32 v6, 25, v6
	v_add_u32_e32 v6, v243, v6
	v_ashrrev_i32_e32 v234, 7, v6
	v_lshlrev_b32_e32 v7, 9, v234
	v_add_u32_e32 v6, s27, v234
	v_sub_u32_e32 v10, v244, v7
	v_ashrrev_i32_e32 v7, 31, v6
	v_lshlrev_b64 v[6:7], 10, v[6:7]
	v_ashrrev_i32_e32 v11, 31, v10
	v_lshl_add_u64 v[12:13], s[8:9], 0, v[6:7]
	v_lshl_add_u64 v[6:7], v[10:11], 2, s[4:5]
	global_load_dwordx4 v[228:231], v[6:7], off
	v_lshl_add_u64 v[10:11], v[10:11], 1, v[12:13]
	global_load_dwordx2 v[232:233], v[10:11], off
	v_add_u32_e32 v243, 0x600, v5
	v_add_u32_e32 v244, 0x1800, v2
	v_ashrrev_i32_e32 v6, 31, v243
	v_lshrrev_b32_e32 v6, 25, v6
	v_add_u32_e32 v6, v243, v6
	v_ashrrev_i32_e32 v242, 7, v6
	v_lshlrev_b32_e32 v7, 9, v242
	v_add_u32_e32 v6, s27, v242
	v_sub_u32_e32 v10, v244, v7
	v_ashrrev_i32_e32 v7, 31, v6
	v_lshlrev_b64 v[6:7], 10, v[6:7]
	v_ashrrev_i32_e32 v11, 31, v10
	v_lshl_add_u64 v[12:13], s[8:9], 0, v[6:7]
	v_lshl_add_u64 v[6:7], v[10:11], 2, s[4:5]
	global_load_dwordx4 v[236:239], v[6:7], off
	v_lshl_add_u64 v[10:11], v[10:11], 1, v[12:13]
	global_load_dwordx2 v[240:241], v[10:11], off
	v_lshl_add_u32 v16, v218, 4, v4
	ds_read_b128 v[10:13], v16
	v_add_u32_e32 v4, 0x2000, v4
	s_waitcnt vmcnt(7) lgkmcnt(0)
	v_add_f32_e32 v6, v10, v212
	v_add_f32_e32 v7, v11, v213
	v_add_f32_e32 v8, v12, v214
	v_add_f32_e32 v9, v13, v215
	v_mul_f32_e32 v10, 0xbfb8aa3b, v6
	v_mul_f32_e32 v11, 0xbfb8aa3b, v7
	v_mul_f32_e32 v8, 0xbfb8aa3b, v8
	v_mul_f32_e32 v9, 0xbfb8aa3b, v9
	v_exp_f32_e32 v10, v10
	v_exp_f32_e32 v11, v11
	v_exp_f32_e32 v8, v8
	v_exp_f32_e32 v9, v9
	v_add_f32_e32 v10, 1.0, v10
	v_add_f32_e32 v11, 1.0, v11
	v_add_f32_e32 v12, 1.0, v8
	v_add_f32_e32 v13, 1.0, v9
	v_rcp_f32_e32 v8, v10
	v_rcp_f32_e32 v9, v11
	v_rcp_f32_e32 v10, v12
	v_rcp_f32_e32 v11, v13
	s_waitcnt vmcnt(6)
	v_lshlrev_b32_e32 v6, 16, v216
	v_and_b32_e32 v7, 0xffff0000, v216
	v_lshlrev_b32_e32 v12, 16, v217
	v_and_b32_e32 v13, 0xffff0000, v217
	v_pk_mul_f32 v[6:7], v[8:9], v[6:7]
	v_pk_mul_f32 v[8:9], v[10:11], v[12:13]
	ds_write_b128 v16, v[6:9]
	v_lshl_add_u32 v16, v226, 4, v4
	ds_read_b128 v[10:13], v16
	v_add_u32_e32 v4, 0x2000, v4
	s_waitcnt vmcnt(5) lgkmcnt(0)
	v_add_f32_e32 v6, v10, v220
	v_add_f32_e32 v7, v11, v221
	v_add_f32_e32 v8, v12, v222
	v_add_f32_e32 v9, v13, v223
	v_mul_f32_e32 v10, 0xbfb8aa3b, v6
	v_mul_f32_e32 v11, 0xbfb8aa3b, v7
	v_mul_f32_e32 v8, 0xbfb8aa3b, v8
	v_mul_f32_e32 v9, 0xbfb8aa3b, v9
	v_exp_f32_e32 v10, v10
	v_exp_f32_e32 v11, v11
	v_exp_f32_e32 v8, v8
	v_exp_f32_e32 v9, v9
	v_add_f32_e32 v10, 1.0, v10
	v_add_f32_e32 v11, 1.0, v11
	v_add_f32_e32 v12, 1.0, v8
	v_add_f32_e32 v13, 1.0, v9
	v_rcp_f32_e32 v8, v10
	v_rcp_f32_e32 v9, v11
	v_rcp_f32_e32 v10, v12
	v_rcp_f32_e32 v11, v13
	s_waitcnt vmcnt(4)
	v_lshlrev_b32_e32 v6, 16, v224
	v_and_b32_e32 v7, 0xffff0000, v224
	v_lshlrev_b32_e32 v12, 16, v225
	v_and_b32_e32 v13, 0xffff0000, v225
	v_pk_mul_f32 v[6:7], v[8:9], v[6:7]
	v_pk_mul_f32 v[8:9], v[10:11], v[12:13]
	ds_write_b128 v16, v[6:9]
	v_lshl_add_u32 v16, v234, 4, v4
	ds_read_b128 v[10:13], v16
	v_add_u32_e32 v4, 0x2000, v4
	s_waitcnt vmcnt(3) lgkmcnt(0)
	v_add_f32_e32 v6, v10, v228
	v_add_f32_e32 v7, v11, v229
	v_add_f32_e32 v8, v12, v230
	v_add_f32_e32 v9, v13, v231
	v_mul_f32_e32 v10, 0xbfb8aa3b, v6
	v_mul_f32_e32 v11, 0xbfb8aa3b, v7
	v_mul_f32_e32 v8, 0xbfb8aa3b, v8
	v_mul_f32_e32 v9, 0xbfb8aa3b, v9
	v_exp_f32_e32 v10, v10
	v_exp_f32_e32 v11, v11
	v_exp_f32_e32 v8, v8
	v_exp_f32_e32 v9, v9
	v_add_f32_e32 v10, 1.0, v10
	v_add_f32_e32 v11, 1.0, v11
	v_add_f32_e32 v12, 1.0, v8
	v_add_f32_e32 v13, 1.0, v9
	v_rcp_f32_e32 v8, v10
	v_rcp_f32_e32 v9, v11
	v_rcp_f32_e32 v10, v12
	v_rcp_f32_e32 v11, v13
	s_waitcnt vmcnt(2)
	v_lshlrev_b32_e32 v6, 16, v232
	v_and_b32_e32 v7, 0xffff0000, v232
	v_lshlrev_b32_e32 v12, 16, v233
	v_and_b32_e32 v13, 0xffff0000, v233
	v_pk_mul_f32 v[6:7], v[8:9], v[6:7]
	v_pk_mul_f32 v[8:9], v[10:11], v[12:13]
	ds_write_b128 v16, v[6:9]
	v_lshl_add_u32 v16, v242, 4, v4
	ds_read_b128 v[10:13], v16
	v_add_u32_e32 v4, 0x2000, v4
	s_waitcnt vmcnt(1) lgkmcnt(0)
	v_add_f32_e32 v6, v10, v236
	v_add_f32_e32 v7, v11, v237
	v_add_f32_e32 v8, v12, v238
	v_add_f32_e32 v9, v13, v239
	v_mul_f32_e32 v10, 0xbfb8aa3b, v6
	v_mul_f32_e32 v11, 0xbfb8aa3b, v7
	v_mul_f32_e32 v8, 0xbfb8aa3b, v8
	v_mul_f32_e32 v9, 0xbfb8aa3b, v9
	v_exp_f32_e32 v10, v10
	v_exp_f32_e32 v11, v11
	v_exp_f32_e32 v8, v8
	v_exp_f32_e32 v9, v9
	v_add_f32_e32 v10, 1.0, v10
	v_add_f32_e32 v11, 1.0, v11
	v_add_f32_e32 v12, 1.0, v8
	v_add_f32_e32 v13, 1.0, v9
	v_rcp_f32_e32 v8, v10
	v_rcp_f32_e32 v9, v11
	v_rcp_f32_e32 v10, v12
	v_rcp_f32_e32 v11, v13
	s_waitcnt vmcnt(0)
	v_lshlrev_b32_e32 v6, 16, v240
	v_and_b32_e32 v7, 0xffff0000, v240
	v_lshlrev_b32_e32 v12, 16, v241
	v_and_b32_e32 v13, 0xffff0000, v241
	v_pk_mul_f32 v[6:7], v[8:9], v[6:7]
	v_pk_mul_f32 v[8:9], v[10:11], v[12:13]
	ds_write_b128 v16, v[6:9]
	v_add_u32_e32 v5, 0x800, v5
	v_add_u32_e32 v2, 0x2000, v2
	s_movk_i32 s28, 0x5ff
